# v140 + one workgroup re-sync barrier at the stage B -> stage C transition (8 waves start the v-table sweep together)
# baseline (speedup 1.0000x reference)
.LBB0_804:
	s_barrier
	v_mov_b32_e32 v0, v175
	s_andn2_b64 vcc, exec, s[56:57]
	s_waitcnt lgkmcnt(0)
	s_cbranch_vccnz .LBB0_761
	v_mov_b32_e32 v170, 0x400
	v_lshlrev_b32_e32 v171, 4, v175
	v_lshlrev_b32_e32 v34, 2, v0
	v_ashrrev_i32_e32 v35, 31, v34
	v_lshlrev_b32_e32 v2, 4, v0
	v_lshlrev_b64 v[0:1], 2, v[34:35]
	v_ashrrev_i32_e32 v3, 31, v2
	v_lshl_add_u64 v[36:37], s[28:29], 0, v[0:1]
	v_lshl_add_u64 v[32:33], s[34:35], 0, v[2:3]
	v_lshl_add_u64 v[38:39], v[36:37], 0, s[46:47]
	v_lshl_add_u64 v[40:41], v[36:37], 0, s[48:49]
	v_lshl_add_u64 v[42:43], v[36:37], 0, s[50:51]
	v_lshl_add_u64 v[44:45], v[36:37], 0, s[52:53]
	v_lshl_add_u64 v[46:47], s[30:31], 0, v[0:1]
	s_mov_b32 s8, 0
	s_mov_b32 s9, s79
	s_mov_b32 s10, s78
	s_branch .LBB0_807
